# prompt attention loop: row-max chain replaced by a conservative sum check (exact max and reference move in a rare out-of-line path), single P buffer
# speedup vs baseline: 1.0470x; 1.0095x over previous
.LBB0_822:
	s_mov_b32 s5, 0
	s_add_i32 s2, s52, 0xfffff000
	buffer_load_dwordx2 v[108:109], v161, s[12:15], s2 offen
	s_add_i32 s3, s53, 0xfe020000
	buffer_load_dwordx4 v[104:107], v150, s[12:15], s3 offen
	s_add_i32 s4, s53, 0xfffe0000
	buffer_load_dwordx4 v[100:103], v150, s[12:15], s4 offen
	ds_read_b64_tr_b16 v[200:201], v162 offset:26624
	ds_read_b64_tr_b16 v[202:203], v162 offset:28160
	ds_read_b64_tr_b16 v[204:205], v162 offset:26688
	ds_read_b64_tr_b16 v[206:207], v162 offset:28224
	ds_read_b64_tr_b16 v[208:209], v162 offset:29696
	ds_read_b64_tr_b16 v[210:211], v162 offset:31232
	ds_read_b64_tr_b16 v[212:213], v162 offset:29760
	ds_read_b64_tr_b16 v[214:215], v162 offset:31296
	v_exp_f32_e32 v184, v84
	v_exp_f32_e32 v216, v36
	v_exp_f32_e32 v185, v85
	v_exp_f32_e32 v217, v37
	s_waitcnt lgkmcnt(6)
	v_mfma_f32_32x32x16_bf16 v[4:19], v[200:203], v[144:147], v[4:19]
	ds_read_b64_tr_b16 v[200:201], v162 offset:32768
	v_add_f32_e32 v224, v184, v216
	v_exp_f32_e32 v186, v86
	v_exp_f32_e32 v218, v38
	v_add_f32_e32 v226, v185, v217
	s_waitcnt lgkmcnt(5)
	v_mfma_f32_32x32x16_bf16 v[20:35], v[204:207], v[144:147], v[20:35]
	ds_read_b64_tr_b16 v[202:203], v162 offset:34304
	ds_read_b64_tr_b16 v[204:205], v162 offset:32832
	v_exp_f32_e32 v187, v87
	v_exp_f32_e32 v219, v39
	v_add_f32_e32 v124, v224, v226
	v_add_f32_e32 v233, v186, v218
	s_waitcnt lgkmcnt(5)
	v_mfma_f32_32x32x16_bf16 v[4:19], v[208:211], v[140:143], v[4:19]
	ds_read_b64_tr_b16 v[206:207], v162 offset:34368
	ds_read_b64_tr_b16 v[208:209], v162 offset:35840
	v_exp_f32_e32 v188, v88
	v_exp_f32_e32 v250, v40
	v_add_f32_e32 v124, v124, v233
	v_add_f32_e32 v224, v187, v219
	s_waitcnt lgkmcnt(5)
	v_mfma_f32_32x32x16_bf16 v[20:35], v[212:215], v[140:143], v[20:35]
	ds_read_b64_tr_b16 v[210:211], v162 offset:37376
	ds_read_b64_tr_b16 v[212:213], v162 offset:35904
	v_exp_f32_e32 v189, v89
	v_exp_f32_e32 v251, v41
	v_add_f32_e32 v124, v124, v224
	v_add_f32_e32 v226, v188, v250
	s_waitcnt lgkmcnt(5)
	v_mfma_f32_32x32x16_bf16 v[4:19], v[200:203], v[136:139], v[4:19]
	ds_read_b64_tr_b16 v[214:215], v162 offset:37440
	ds_read_b128 v[164:167], v156 offset:51200
	v_exp_f32_e32 v190, v90
	v_exp_f32_e32 v252, v42
	v_add_f32_e32 v124, v124, v226
	v_add_f32_e32 v233, v189, v251
	s_waitcnt lgkmcnt(5)
	v_mfma_f32_32x32x16_bf16 v[20:35], v[204:207], v[136:139], v[20:35]
	ds_read_b128 v[176:179], v155 offset:0
	ds_read_b128 v[180:183], v155 offset:6656
	v_exp_f32_e32 v191, v91
	v_exp_f32_e32 v253, v43
	v_add_f32_e32 v124, v124, v233
	v_add_f32_e32 v224, v190, v252
	s_waitcnt lgkmcnt(5)
	v_mfma_f32_32x32x16_bf16 v[4:19], v[208:211], v[132:135], v[4:19]
	ds_read_b128 v[168:171], v156 offset:51232
	ds_read_b128 v[112:115], v155 offset:32
	v_exp_f32_e32 v192, v92
	v_exp_f32_e32 v125, v44
	v_add_f32_e32 v124, v124, v224
	v_add_f32_e32 v226, v191, v253
	s_waitcnt lgkmcnt(5)
	v_mfma_f32_32x32x16_bf16 v[20:35], v[212:215], v[132:135], v[20:35]
	ds_read_b128 v[116:119], v155 offset:6688
	ds_read_b128 v[172:175], v156 offset:51264
	v_exp_f32_e32 v193, v93
	v_exp_f32_e32 v126, v45
	v_add_f32_e32 v124, v124, v226
	v_add_f32_e32 v233, v192, v125
	s_waitcnt lgkmcnt(5)
	v_mfma_f32_32x32x16_bf16 v[52:67], v[176:179], v[164:167], v[234:249]
	ds_read_b128 v[120:123], v155 offset:64
	ds_read_b128 v[176:179], v155 offset:6720
	v_exp_f32_e32 v194, v94
	v_exp_f32_e32 v127, v46
	v_add_f32_e32 v124, v124, v233
	v_add_f32_e32 v224, v193, v126
	s_waitcnt lgkmcnt(6)
	v_mfma_f32_32x32x16_bf16 v[68:83], v[180:183], v[164:167], v[234:249]
	ds_read_b128 v[164:167], v156 offset:51296
	v_exp_f32_e32 v195, v95
	v_exp_f32_e32 v128, v47
	v_add_f32_e32 v124, v124, v224
	v_add_f32_e32 v226, v194, v127
	s_waitcnt lgkmcnt(5)
	v_mfma_f32_32x32x16_bf16 v[52:67], v[112:115], v[168:171], v[52:67]
	ds_read_b128 v[180:183], v155 offset:96
	ds_read_b128 v[112:115], v155 offset:6752
	v_exp_f32_e32 v196, v96
	v_exp_f32_e32 v129, v48
	v_add_f32_e32 v124, v124, v226
	v_add_f32_e32 v233, v195, v128
	s_waitcnt lgkmcnt(6)
	v_mfma_f32_32x32x16_bf16 v[68:83], v[116:119], v[168:171], v[68:83]
	ds_read_b128 v[168:171], v156 offset:51328
	v_exp_f32_e32 v197, v97
	v_exp_f32_e32 v130, v49
	v_add_f32_e32 v124, v124, v233
	v_add_f32_e32 v224, v196, v129
	s_waitcnt lgkmcnt(5)
	v_mfma_f32_32x32x16_bf16 v[52:67], v[120:123], v[172:175], v[52:67]
	ds_read_b128 v[116:119], v155 offset:128
	ds_read_b128 v[120:123], v155 offset:6784
	v_exp_f32_e32 v198, v98
	v_exp_f32_e32 v131, v50
	v_add_f32_e32 v124, v124, v224
	v_add_f32_e32 v226, v197, v130
	s_waitcnt lgkmcnt(6)
	v_mfma_f32_32x32x16_bf16 v[68:83], v[176:179], v[172:175], v[68:83]
	ds_read_b128 v[172:175], v156 offset:51360
	v_exp_f32_e32 v199, v99
	v_exp_f32_e32 v254, v51
	v_add_f32_e32 v124, v124, v226
	v_add_f32_e32 v233, v198, v131
	s_waitcnt lgkmcnt(5)
	v_mfma_f32_32x32x16_bf16 v[52:67], v[180:183], v[164:167], v[52:67]
	ds_read_b128 v[176:179], v155 offset:160
	ds_read_b128 v[180:183], v155 offset:6816
	v_add_f32_e32 v124, v124, v233
	v_add_f32_e32 v224, v199, v254
	v_add_f32_e32 v124, v124, v224
	v_cmp_lt_f32_e32 vcc, 0x43800000, v124
	s_cbranch_vccnz .Lpc_s0
.Lpc_b0:
	s_waitcnt lgkmcnt(6)
	v_mfma_f32_32x32x16_bf16 v[68:83], v[112:115], v[164:167], v[68:83]
	v_cvt_pk_bf16_f32 v144, v184, v185
	v_cvt_pk_bf16_f32 v145, v186, v187
	v_cvt_pk_bf16_f32 v146, v188, v189
	v_cvt_pk_bf16_f32 v147, v190, v191
	s_waitcnt lgkmcnt(4)
	v_mfma_f32_32x32x16_bf16 v[52:67], v[116:119], v[168:171], v[52:67]
	v_cvt_pk_bf16_f32 v140, v192, v193
	v_cvt_pk_bf16_f32 v141, v194, v195
	v_cvt_pk_bf16_f32 v142, v196, v197
	v_cvt_pk_bf16_f32 v143, v198, v199
	s_waitcnt lgkmcnt(3)
	v_mfma_f32_32x32x16_bf16 v[68:83], v[120:123], v[168:171], v[68:83]
	v_cvt_pk_bf16_f32 v136, v216, v217
	v_cvt_pk_bf16_f32 v137, v218, v219
	v_cvt_pk_bf16_f32 v138, v250, v251
	v_cvt_pk_bf16_f32 v139, v252, v253
	s_waitcnt lgkmcnt(1)
	v_mfma_f32_32x32x16_bf16 v[52:67], v[176:179], v[172:175], v[52:67]
	v_cvt_pk_bf16_f32 v132, v125, v126
	v_cvt_pk_bf16_f32 v133, v127, v128
	v_cvt_pk_bf16_f32 v134, v129, v130
	v_cvt_pk_bf16_f32 v135, v131, v254
	s_waitcnt lgkmcnt(0)
	v_mfma_f32_32x32x16_bf16 v[68:83], v[180:183], v[172:175], v[68:83]
	v_add_f32_e32 v152, v152, v124
	s_cmp_eq_u32 s5, 0
	s_cbranch_scc1 .Lpc_nr0
	s_nop 11
	v_pk_mul_f32 v[4:5], v[220:221], v[4:5] op_sel_hi:[0,1]
	v_pk_mul_f32 v[6:7], v[220:221], v[6:7] op_sel_hi:[0,1]
	v_pk_mul_f32 v[8:9], v[220:221], v[8:9] op_sel_hi:[0,1]
	v_pk_mul_f32 v[10:11], v[220:221], v[10:11] op_sel_hi:[0,1]
	v_pk_mul_f32 v[12:13], v[220:221], v[12:13] op_sel_hi:[0,1]
	v_pk_mul_f32 v[14:15], v[220:221], v[14:15] op_sel_hi:[0,1]
	v_pk_mul_f32 v[16:17], v[220:221], v[16:17] op_sel_hi:[0,1]
	v_pk_mul_f32 v[18:19], v[220:221], v[18:19] op_sel_hi:[0,1]
	v_pk_mul_f32 v[20:21], v[220:221], v[20:21] op_sel_hi:[0,1]
	v_pk_mul_f32 v[22:23], v[220:221], v[22:23] op_sel_hi:[0,1]
	v_pk_mul_f32 v[24:25], v[220:221], v[24:25] op_sel_hi:[0,1]
	v_pk_mul_f32 v[26:27], v[220:221], v[26:27] op_sel_hi:[0,1]
	v_pk_mul_f32 v[28:29], v[220:221], v[28:29] op_sel_hi:[0,1]
	v_pk_mul_f32 v[30:31], v[220:221], v[30:31] op_sel_hi:[0,1]
	v_pk_mul_f32 v[32:33], v[220:221], v[32:33] op_sel_hi:[0,1]
	v_pk_mul_f32 v[34:35], v[220:221], v[34:35] op_sel_hi:[0,1]
	v_sub_f32_e32 v52, v52, v222
	v_sub_f32_e32 v68, v68, v222
	v_sub_f32_e32 v53, v53, v222
	v_sub_f32_e32 v69, v69, v222
	v_sub_f32_e32 v54, v54, v222
	v_sub_f32_e32 v70, v70, v222
	v_sub_f32_e32 v55, v55, v222
	v_sub_f32_e32 v71, v71, v222
	v_sub_f32_e32 v56, v56, v222
	v_sub_f32_e32 v72, v72, v222
	v_sub_f32_e32 v57, v57, v222
	v_sub_f32_e32 v73, v73, v222
	v_sub_f32_e32 v58, v58, v222
	v_sub_f32_e32 v74, v74, v222
	v_sub_f32_e32 v59, v59, v222
	v_sub_f32_e32 v75, v75, v222
	v_sub_f32_e32 v60, v60, v222
	v_sub_f32_e32 v76, v76, v222
	v_sub_f32_e32 v61, v61, v222
	v_sub_f32_e32 v77, v77, v222
	v_sub_f32_e32 v62, v62, v222
	v_sub_f32_e32 v78, v78, v222
	v_sub_f32_e32 v63, v63, v222
	v_sub_f32_e32 v79, v79, v222
	v_sub_f32_e32 v64, v64, v222
	v_sub_f32_e32 v80, v80, v222
	v_sub_f32_e32 v65, v65, v222
	v_sub_f32_e32 v81, v81, v222
	v_sub_f32_e32 v66, v66, v222
	v_sub_f32_e32 v82, v82, v222
	v_sub_f32_e32 v67, v67, v222
	v_sub_f32_e32 v83, v83, v222
	v_sub_f32_e32 v234, v234, v222
	v_sub_f32_e32 v235, v235, v222
	v_sub_f32_e32 v236, v236, v222
	v_sub_f32_e32 v237, v237, v222
	v_sub_f32_e32 v238, v238, v222
	v_sub_f32_e32 v239, v239, v222
	v_sub_f32_e32 v240, v240, v222
	v_sub_f32_e32 v241, v241, v222
	v_sub_f32_e32 v242, v242, v222
	v_sub_f32_e32 v243, v243, v222
	v_sub_f32_e32 v244, v244, v222
	v_sub_f32_e32 v245, v245, v222
	v_sub_f32_e32 v246, v246, v222
	v_sub_f32_e32 v247, v247, v222
	v_sub_f32_e32 v248, v248, v222
	v_sub_f32_e32 v249, v249, v222
.Lpc_nr0:
	s_waitcnt vmcnt(1)
	ds_write_b128 v157, v[104:107] offset:13312
	ds_write_b64 v158, v[108:109] offset:13440
	s_waitcnt vmcnt(0)
	ds_write_b128 v151, v[100:103] offset:38912
	s_waitcnt lgkmcnt(0)
	s_barrier
	s_mov_b32 s5, 0
	buffer_load_dwordx2 v[108:109], v161, s[12:15], s52 offen
	s_add_i32 s3, s53, 0xfe040000
	buffer_load_dwordx4 v[104:107], v150, s[12:15], s3 offen
	buffer_load_dwordx4 v[100:103], v150, s[12:15], s53 offen
	ds_read_b64_tr_b16 v[200:201], v162 offset:38912
	ds_read_b64_tr_b16 v[202:203], v162 offset:40448
	ds_read_b64_tr_b16 v[204:205], v162 offset:38976
	ds_read_b64_tr_b16 v[206:207], v162 offset:40512
	ds_read_b64_tr_b16 v[208:209], v162 offset:41984
	ds_read_b64_tr_b16 v[210:211], v162 offset:43520
	ds_read_b64_tr_b16 v[212:213], v162 offset:42048
	ds_read_b64_tr_b16 v[214:215], v162 offset:43584
	v_exp_f32_e32 v184, v52
	v_exp_f32_e32 v216, v68
	v_exp_f32_e32 v185, v53
	v_exp_f32_e32 v217, v69
	s_waitcnt lgkmcnt(6)
	v_mfma_f32_32x32x16_bf16 v[4:19], v[200:203], v[144:147], v[4:19]
	ds_read_b64_tr_b16 v[200:201], v162 offset:45056
	v_add_f32_e32 v224, v184, v216
	v_exp_f32_e32 v186, v54
	v_exp_f32_e32 v218, v70
	v_add_f32_e32 v226, v185, v217
	s_waitcnt lgkmcnt(5)
	v_mfma_f32_32x32x16_bf16 v[20:35], v[204:207], v[144:147], v[20:35]
	ds_read_b64_tr_b16 v[202:203], v162 offset:46592
	ds_read_b64_tr_b16 v[204:205], v162 offset:45120
	v_exp_f32_e32 v187, v55
	v_exp_f32_e32 v219, v71
	v_add_f32_e32 v124, v224, v226
	v_add_f32_e32 v233, v186, v218
	s_waitcnt lgkmcnt(5)
	v_mfma_f32_32x32x16_bf16 v[4:19], v[208:211], v[140:143], v[4:19]
	ds_read_b64_tr_b16 v[206:207], v162 offset:46656
	ds_read_b64_tr_b16 v[208:209], v162 offset:48128
	v_exp_f32_e32 v188, v56
	v_exp_f32_e32 v250, v72
	v_add_f32_e32 v124, v124, v233
	v_add_f32_e32 v224, v187, v219
	s_waitcnt lgkmcnt(5)
	v_mfma_f32_32x32x16_bf16 v[20:35], v[212:215], v[140:143], v[20:35]
	ds_read_b64_tr_b16 v[210:211], v162 offset:49664
	ds_read_b64_tr_b16 v[212:213], v162 offset:48192
	v_exp_f32_e32 v189, v57
	v_exp_f32_e32 v251, v73
	v_add_f32_e32 v124, v124, v224
	v_add_f32_e32 v226, v188, v250
	s_waitcnt lgkmcnt(5)
	v_mfma_f32_32x32x16_bf16 v[4:19], v[200:203], v[136:139], v[4:19]
	ds_read_b64_tr_b16 v[214:215], v162 offset:49728
	ds_read_b128 v[164:167], v156 offset:51200
	v_exp_f32_e32 v190, v58
	v_exp_f32_e32 v252, v74
	v_add_f32_e32 v124, v124, v226
	v_add_f32_e32 v233, v189, v251
	s_waitcnt lgkmcnt(5)
	v_mfma_f32_32x32x16_bf16 v[20:35], v[204:207], v[136:139], v[20:35]
	ds_read_b128 v[176:179], v155 offset:13312
	ds_read_b128 v[180:183], v155 offset:19968
	v_exp_f32_e32 v191, v59
	v_exp_f32_e32 v253, v75
	v_add_f32_e32 v124, v124, v233
	v_add_f32_e32 v224, v190, v252
	s_waitcnt lgkmcnt(5)
	v_mfma_f32_32x32x16_bf16 v[4:19], v[208:211], v[132:135], v[4:19]
	ds_read_b128 v[168:171], v156 offset:51232
	ds_read_b128 v[112:115], v155 offset:13344
	v_exp_f32_e32 v192, v60
	v_exp_f32_e32 v125, v76
	v_add_f32_e32 v124, v124, v224
	v_add_f32_e32 v226, v191, v253
	s_waitcnt lgkmcnt(5)
	v_mfma_f32_32x32x16_bf16 v[20:35], v[212:215], v[132:135], v[20:35]
	ds_read_b128 v[116:119], v155 offset:20000
	ds_read_b128 v[172:175], v156 offset:51264
	v_exp_f32_e32 v193, v61
	v_exp_f32_e32 v126, v77
	v_add_f32_e32 v124, v124, v226
	v_add_f32_e32 v233, v192, v125
	s_waitcnt lgkmcnt(5)
	v_mfma_f32_32x32x16_bf16 v[84:99], v[176:179], v[164:167], v[234:249]
	ds_read_b128 v[120:123], v155 offset:13376
	ds_read_b128 v[176:179], v155 offset:20032
	v_exp_f32_e32 v194, v62
	v_exp_f32_e32 v127, v78
	v_add_f32_e32 v124, v124, v233
	v_add_f32_e32 v224, v193, v126
	s_waitcnt lgkmcnt(6)
	v_mfma_f32_32x32x16_bf16 v[36:51], v[180:183], v[164:167], v[234:249]
	ds_read_b128 v[164:167], v156 offset:51296
	v_exp_f32_e32 v195, v63
	v_exp_f32_e32 v128, v79
	v_add_f32_e32 v124, v124, v224
	v_add_f32_e32 v226, v194, v127
	s_waitcnt lgkmcnt(5)
	v_mfma_f32_32x32x16_bf16 v[84:99], v[112:115], v[168:171], v[84:99]
	ds_read_b128 v[180:183], v155 offset:13408
	ds_read_b128 v[112:115], v155 offset:20064
	v_exp_f32_e32 v196, v64
	v_exp_f32_e32 v129, v80
	v_add_f32_e32 v124, v124, v226
	v_add_f32_e32 v233, v195, v128
	s_waitcnt lgkmcnt(6)
	v_mfma_f32_32x32x16_bf16 v[36:51], v[116:119], v[168:171], v[36:51]
	ds_read_b128 v[168:171], v156 offset:51328
	v_exp_f32_e32 v197, v65
	v_exp_f32_e32 v130, v81
	v_add_f32_e32 v124, v124, v233
	v_add_f32_e32 v224, v196, v129
	s_waitcnt lgkmcnt(5)
	v_mfma_f32_32x32x16_bf16 v[84:99], v[120:123], v[172:175], v[84:99]
	ds_read_b128 v[116:119], v155 offset:13440
	ds_read_b128 v[120:123], v155 offset:20096
	v_exp_f32_e32 v198, v66
	v_exp_f32_e32 v131, v82
	v_add_f32_e32 v124, v124, v224
	v_add_f32_e32 v226, v197, v130
	s_waitcnt lgkmcnt(6)
	v_mfma_f32_32x32x16_bf16 v[36:51], v[176:179], v[172:175], v[36:51]
	ds_read_b128 v[172:175], v156 offset:51360
	v_exp_f32_e32 v199, v67
	v_exp_f32_e32 v254, v83
	v_add_f32_e32 v124, v124, v226
	v_add_f32_e32 v233, v198, v131
	s_waitcnt lgkmcnt(5)
	v_mfma_f32_32x32x16_bf16 v[84:99], v[180:183], v[164:167], v[84:99]
	ds_read_b128 v[176:179], v155 offset:13472
	ds_read_b128 v[180:183], v155 offset:20128
	v_add_f32_e32 v124, v124, v233
	v_add_f32_e32 v224, v199, v254
	v_add_f32_e32 v124, v124, v224
	v_cmp_lt_f32_e32 vcc, 0x43800000, v124
	s_cbranch_vccnz .Lpc_s1
.Lpc_b1:
	s_waitcnt lgkmcnt(6)
	v_mfma_f32_32x32x16_bf16 v[36:51], v[112:115], v[164:167], v[36:51]
	v_cvt_pk_bf16_f32 v144, v184, v185
	v_cvt_pk_bf16_f32 v145, v186, v187
	v_cvt_pk_bf16_f32 v146, v188, v189
	v_cvt_pk_bf16_f32 v147, v190, v191
	s_waitcnt lgkmcnt(4)
	v_mfma_f32_32x32x16_bf16 v[84:99], v[116:119], v[168:171], v[84:99]
	v_cvt_pk_bf16_f32 v140, v192, v193
	v_cvt_pk_bf16_f32 v141, v194, v195
	v_cvt_pk_bf16_f32 v142, v196, v197
	v_cvt_pk_bf16_f32 v143, v198, v199
	s_waitcnt lgkmcnt(3)
	v_mfma_f32_32x32x16_bf16 v[36:51], v[120:123], v[168:171], v[36:51]
	v_cvt_pk_bf16_f32 v136, v216, v217
	v_cvt_pk_bf16_f32 v137, v218, v219
	v_cvt_pk_bf16_f32 v138, v250, v251
	v_cvt_pk_bf16_f32 v139, v252, v253
	s_waitcnt lgkmcnt(1)
	v_mfma_f32_32x32x16_bf16 v[84:99], v[176:179], v[172:175], v[84:99]
	v_cvt_pk_bf16_f32 v132, v125, v126
	v_cvt_pk_bf16_f32 v133, v127, v128
	v_cvt_pk_bf16_f32 v134, v129, v130
	v_cvt_pk_bf16_f32 v135, v131, v254
	s_waitcnt lgkmcnt(0)
	v_mfma_f32_32x32x16_bf16 v[36:51], v[180:183], v[172:175], v[36:51]
	v_add_f32_e32 v152, v152, v124
	s_cmp_eq_u32 s5, 0
	s_cbranch_scc1 .Lpc_nr1
	s_nop 11
	v_pk_mul_f32 v[4:5], v[220:221], v[4:5] op_sel_hi:[0,1]
	v_pk_mul_f32 v[6:7], v[220:221], v[6:7] op_sel_hi:[0,1]
	v_pk_mul_f32 v[8:9], v[220:221], v[8:9] op_sel_hi:[0,1]
	v_pk_mul_f32 v[10:11], v[220:221], v[10:11] op_sel_hi:[0,1]
	v_pk_mul_f32 v[12:13], v[220:221], v[12:13] op_sel_hi:[0,1]
	v_pk_mul_f32 v[14:15], v[220:221], v[14:15] op_sel_hi:[0,1]
	v_pk_mul_f32 v[16:17], v[220:221], v[16:17] op_sel_hi:[0,1]
	v_pk_mul_f32 v[18:19], v[220:221], v[18:19] op_sel_hi:[0,1]
	v_pk_mul_f32 v[20:21], v[220:221], v[20:21] op_sel_hi:[0,1]
	v_pk_mul_f32 v[22:23], v[220:221], v[22:23] op_sel_hi:[0,1]
	v_pk_mul_f32 v[24:25], v[220:221], v[24:25] op_sel_hi:[0,1]
	v_pk_mul_f32 v[26:27], v[220:221], v[26:27] op_sel_hi:[0,1]
	v_pk_mul_f32 v[28:29], v[220:221], v[28:29] op_sel_hi:[0,1]
	v_pk_mul_f32 v[30:31], v[220:221], v[30:31] op_sel_hi:[0,1]
	v_pk_mul_f32 v[32:33], v[220:221], v[32:33] op_sel_hi:[0,1]
	v_pk_mul_f32 v[34:35], v[220:221], v[34:35] op_sel_hi:[0,1]
	v_sub_f32_e32 v84, v84, v222
	v_sub_f32_e32 v36, v36, v222
	v_sub_f32_e32 v85, v85, v222
	v_sub_f32_e32 v37, v37, v222
	v_sub_f32_e32 v86, v86, v222
	v_sub_f32_e32 v38, v38, v222
	v_sub_f32_e32 v87, v87, v222
	v_sub_f32_e32 v39, v39, v222
	v_sub_f32_e32 v88, v88, v222
	v_sub_f32_e32 v40, v40, v222
	v_sub_f32_e32 v89, v89, v222
	v_sub_f32_e32 v41, v41, v222
	v_sub_f32_e32 v90, v90, v222
	v_sub_f32_e32 v42, v42, v222
	v_sub_f32_e32 v91, v91, v222
	v_sub_f32_e32 v43, v43, v222
	v_sub_f32_e32 v92, v92, v222
	v_sub_f32_e32 v44, v44, v222
	v_sub_f32_e32 v93, v93, v222
	v_sub_f32_e32 v45, v45, v222
	v_sub_f32_e32 v94, v94, v222
	v_sub_f32_e32 v46, v46, v222
	v_sub_f32_e32 v95, v95, v222
	v_sub_f32_e32 v47, v47, v222
	v_sub_f32_e32 v96, v96, v222
	v_sub_f32_e32 v48, v48, v222
	v_sub_f32_e32 v97, v97, v222
	v_sub_f32_e32 v49, v49, v222
	v_sub_f32_e32 v98, v98, v222
	v_sub_f32_e32 v50, v50, v222
	v_sub_f32_e32 v99, v99, v222
	v_sub_f32_e32 v51, v51, v222
	v_sub_f32_e32 v234, v234, v222
	v_sub_f32_e32 v235, v235, v222
	v_sub_f32_e32 v236, v236, v222
	v_sub_f32_e32 v237, v237, v222
	v_sub_f32_e32 v238, v238, v222
	v_sub_f32_e32 v239, v239, v222
	v_sub_f32_e32 v240, v240, v222
	v_sub_f32_e32 v241, v241, v222
	v_sub_f32_e32 v242, v242, v222
	v_sub_f32_e32 v243, v243, v222
	v_sub_f32_e32 v244, v244, v222
	v_sub_f32_e32 v245, v245, v222
	v_sub_f32_e32 v246, v246, v222
	v_sub_f32_e32 v247, v247, v222
	v_sub_f32_e32 v248, v248, v222
	v_sub_f32_e32 v249, v249, v222

.Lpc_s0:
	v_max3_f32 v2, v84, v36, v85
	v_max3_f32 v110, v37, v86, v38
	v_max3_f32 v2, v2, v87, v39
	v_max3_f32 v110, v110, v88, v40
	v_max3_f32 v2, v2, v89, v41
	v_max3_f32 v110, v110, v90, v42
	v_max3_f32 v2, v2, v91, v43
	v_max3_f32 v110, v110, v92, v44
	v_max3_f32 v2, v2, v93, v45
	v_max3_f32 v110, v110, v94, v46
	v_max3_f32 v2, v2, v95, v47
	v_max3_f32 v110, v110, v96, v48
	v_max3_f32 v2, v2, v97, v49
	v_max3_f32 v110, v110, v98, v50
	v_max3_f32 v2, v2, v110, v99
	v_max_f32_e32 v2, v2, v51
	v_mov_b32_e32 v111, v2
	s_nop 1
	v_permlane32_swap_b32_e32 v2, v111
	v_max_f32_e32 v2, v2, v111
	v_max_f32_e32 v222, 0, v2
	s_mov_b32 s5, 1
	v_exp_f32_e64 v220, -v222
	v_add_f32_e32 v159, v159, v222
	v_sub_f32_e32 v84, v84, v222
	v_sub_f32_e32 v36, v36, v222
	v_sub_f32_e32 v85, v85, v222
	v_sub_f32_e32 v37, v37, v222
	v_sub_f32_e32 v86, v86, v222
	v_sub_f32_e32 v38, v38, v222
	v_sub_f32_e32 v87, v87, v222
	v_sub_f32_e32 v39, v39, v222
	v_sub_f32_e32 v88, v88, v222
	v_sub_f32_e32 v40, v40, v222
	v_sub_f32_e32 v89, v89, v222
	v_sub_f32_e32 v41, v41, v222
	v_sub_f32_e32 v90, v90, v222
	v_sub_f32_e32 v42, v42, v222
	v_sub_f32_e32 v91, v91, v222
	v_sub_f32_e32 v43, v43, v222
	v_sub_f32_e32 v92, v92, v222
	v_sub_f32_e32 v44, v44, v222
	v_sub_f32_e32 v93, v93, v222
	v_sub_f32_e32 v45, v45, v222
	v_sub_f32_e32 v94, v94, v222
	v_sub_f32_e32 v46, v46, v222
	v_sub_f32_e32 v95, v95, v222
	v_sub_f32_e32 v47, v47, v222
	v_sub_f32_e32 v96, v96, v222
	v_sub_f32_e32 v48, v48, v222
	v_sub_f32_e32 v97, v97, v222
	v_sub_f32_e32 v49, v49, v222
	v_sub_f32_e32 v98, v98, v222
	v_sub_f32_e32 v50, v50, v222
	v_sub_f32_e32 v99, v99, v222
	v_sub_f32_e32 v51, v51, v222
	v_mul_f32_e32 v152, v152, v220
	v_exp_f32_e32 v184, v84
	v_exp_f32_e32 v216, v36
	v_exp_f32_e32 v185, v85
	v_exp_f32_e32 v217, v37
	v_exp_f32_e32 v186, v86
	v_exp_f32_e32 v218, v38
	v_exp_f32_e32 v187, v87
	v_exp_f32_e32 v219, v39
	v_exp_f32_e32 v188, v88
	v_exp_f32_e32 v250, v40
	v_exp_f32_e32 v189, v89
	v_exp_f32_e32 v251, v41
	v_exp_f32_e32 v190, v90
	v_exp_f32_e32 v252, v42
	v_exp_f32_e32 v191, v91
	v_exp_f32_e32 v253, v43
	v_exp_f32_e32 v192, v92
	v_exp_f32_e32 v125, v44
	v_exp_f32_e32 v193, v93
	v_exp_f32_e32 v126, v45
	v_exp_f32_e32 v194, v94
	v_exp_f32_e32 v127, v46
	v_exp_f32_e32 v195, v95
	v_exp_f32_e32 v128, v47
	v_exp_f32_e32 v196, v96
	v_exp_f32_e32 v129, v48
	v_exp_f32_e32 v197, v97
	v_exp_f32_e32 v130, v49
	v_exp_f32_e32 v198, v98
	v_exp_f32_e32 v131, v50
	v_exp_f32_e32 v199, v99
	v_exp_f32_e32 v254, v51
	s_nop 0
	v_add_f32_e32 v124, v184, v216
	v_add_f32_e32 v111, v185, v217
	v_add_f32_e32 v124, v124, v111
	v_add_f32_e32 v111, v186, v218
	v_add_f32_e32 v124, v124, v111
	v_add_f32_e32 v111, v187, v219
	v_add_f32_e32 v124, v124, v111
	v_add_f32_e32 v111, v188, v250
	v_add_f32_e32 v124, v124, v111
	v_add_f32_e32 v111, v189, v251
	v_add_f32_e32 v124, v124, v111
	v_add_f32_e32 v111, v190, v252
	v_add_f32_e32 v124, v124, v111
	v_add_f32_e32 v111, v191, v253
	v_add_f32_e32 v124, v124, v111
	v_add_f32_e32 v111, v192, v125
	v_add_f32_e32 v124, v124, v111
	v_add_f32_e32 v111, v193, v126
	v_add_f32_e32 v124, v124, v111
	v_add_f32_e32 v111, v194, v127
	v_add_f32_e32 v124, v124, v111
	v_add_f32_e32 v111, v195, v128
	v_add_f32_e32 v124, v124, v111
	v_add_f32_e32 v111, v196, v129
	v_add_f32_e32 v124, v124, v111
	v_add_f32_e32 v111, v197, v130
	v_add_f32_e32 v124, v124, v111
	v_add_f32_e32 v111, v198, v131
	v_add_f32_e32 v124, v124, v111
	v_add_f32_e32 v111, v199, v254
	v_add_f32_e32 v124, v124, v111
	s_branch .Lpc_b0
.Lpc_s1:
	v_max3_f32 v2, v52, v68, v53
	v_max3_f32 v110, v69, v54, v70
	v_max3_f32 v2, v2, v55, v71
	v_max3_f32 v110, v110, v56, v72
	v_max3_f32 v2, v2, v57, v73
	v_max3_f32 v110, v110, v58, v74
	v_max3_f32 v2, v2, v59, v75
	v_max3_f32 v110, v110, v60, v76
	v_max3_f32 v2, v2, v61, v77
	v_max3_f32 v110, v110, v62, v78
	v_max3_f32 v2, v2, v63, v79
	v_max3_f32 v110, v110, v64, v80
	v_max3_f32 v2, v2, v65, v81
	v_max3_f32 v110, v110, v66, v82
	v_max3_f32 v2, v2, v110, v67
	v_max_f32_e32 v2, v2, v83
	v_mov_b32_e32 v111, v2
	s_nop 1
	v_permlane32_swap_b32_e32 v2, v111
	v_max_f32_e32 v2, v2, v111
	v_max_f32_e32 v222, 0, v2
	s_mov_b32 s5, 1
	v_exp_f32_e64 v220, -v222
	v_add_f32_e32 v159, v159, v222
	v_sub_f32_e32 v52, v52, v222
	v_sub_f32_e32 v68, v68, v222
	v_sub_f32_e32 v53, v53, v222
	v_sub_f32_e32 v69, v69, v222
	v_sub_f32_e32 v54, v54, v222
	v_sub_f32_e32 v70, v70, v222
	v_sub_f32_e32 v55, v55, v222
	v_sub_f32_e32 v71, v71, v222
	v_sub_f32_e32 v56, v56, v222
	v_sub_f32_e32 v72, v72, v222
	v_sub_f32_e32 v57, v57, v222
	v_sub_f32_e32 v73, v73, v222
	v_sub_f32_e32 v58, v58, v222
	v_sub_f32_e32 v74, v74, v222
	v_sub_f32_e32 v59, v59, v222
	v_sub_f32_e32 v75, v75, v222
	v_sub_f32_e32 v60, v60, v222
	v_sub_f32_e32 v76, v76, v222
	v_sub_f32_e32 v61, v61, v222
	v_sub_f32_e32 v77, v77, v222
	v_sub_f32_e32 v62, v62, v222
	v_sub_f32_e32 v78, v78, v222
	v_sub_f32_e32 v63, v63, v222
	v_sub_f32_e32 v79, v79, v222
	v_sub_f32_e32 v64, v64, v222
	v_sub_f32_e32 v80, v80, v222
	v_sub_f32_e32 v65, v65, v222
	v_sub_f32_e32 v81, v81, v222
	v_sub_f32_e32 v66, v66, v222
	v_sub_f32_e32 v82, v82, v222
	v_sub_f32_e32 v67, v67, v222
	v_sub_f32_e32 v83, v83, v222
	v_mul_f32_e32 v152, v152, v220
	v_exp_f32_e32 v184, v52
	v_exp_f32_e32 v216, v68
	v_exp_f32_e32 v185, v53
	v_exp_f32_e32 v217, v69
	v_exp_f32_e32 v186, v54
	v_exp_f32_e32 v218, v70
	v_exp_f32_e32 v187, v55
	v_exp_f32_e32 v219, v71
	v_exp_f32_e32 v188, v56
	v_exp_f32_e32 v250, v72
	v_exp_f32_e32 v189, v57
	v_exp_f32_e32 v251, v73
	v_exp_f32_e32 v190, v58
	v_exp_f32_e32 v252, v74
	v_exp_f32_e32 v191, v59
	v_exp_f32_e32 v253, v75
	v_exp_f32_e32 v192, v60
	v_exp_f32_e32 v125, v76
	v_exp_f32_e32 v193, v61
	v_exp_f32_e32 v126, v77
	v_exp_f32_e32 v194, v62
	v_exp_f32_e32 v127, v78
	v_exp_f32_e32 v195, v63
	v_exp_f32_e32 v128, v79
	v_exp_f32_e32 v196, v64
	v_exp_f32_e32 v129, v80
	v_exp_f32_e32 v197, v65
	v_exp_f32_e32 v130, v81
	v_exp_f32_e32 v198, v66
	v_exp_f32_e32 v131, v82
	v_exp_f32_e32 v199, v67
	v_exp_f32_e32 v254, v83
	s_nop 0
	v_add_f32_e32 v124, v184, v216
	v_add_f32_e32 v111, v185, v217
	v_add_f32_e32 v124, v124, v111
	v_add_f32_e32 v111, v186, v218
	v_add_f32_e32 v124, v124, v111
	v_add_f32_e32 v111, v187, v219
	v_add_f32_e32 v124, v124, v111
	v_add_f32_e32 v111, v188, v250
	v_add_f32_e32 v124, v124, v111
	v_add_f32_e32 v111, v189, v251
	v_add_f32_e32 v124, v124, v111
	v_add_f32_e32 v111, v190, v252
	v_add_f32_e32 v124, v124, v111
	v_add_f32_e32 v111, v191, v253
	v_add_f32_e32 v124, v124, v111
	v_add_f32_e32 v111, v192, v125
	v_add_f32_e32 v124, v124, v111
	v_add_f32_e32 v111, v193, v126
	v_add_f32_e32 v124, v124, v111
	v_add_f32_e32 v111, v194, v127
	v_add_f32_e32 v124, v124, v111
	v_add_f32_e32 v111, v195, v128
	v_add_f32_e32 v124, v124, v111
	v_add_f32_e32 v111, v196, v129
	v_add_f32_e32 v124, v124, v111
	v_add_f32_e32 v111, v197, v130
	v_add_f32_e32 v124, v124, v111
	v_add_f32_e32 v111, v198, v131
	v_add_f32_e32 v124, v124, v111
	v_add_f32_e32 v111, v199, v254
	v_add_f32_e32 v124, v124, v111
	s_branch .Lpc_b1
